# version 97 plus residual epilogue: row-sum reductions and float atomics of row groups 0-6 issued before the last group's compute, only the last group's atomic at the end
# speedup vs baseline: 1.0011x; 1.0011x over previous
; #define PG8_STAGE(bufoff, gbase, voff) do { _Pragma("unroll") for (int _i = 0; _i < 2; ++_i) \
;         __builtin_amdgcn_global_load_lds((const unsigned*)((const char*)(gbase) + (voff)[_i]), (PG8_LAS unsigned*)(lds + (bufoff) + ldsw + _i * 8192), 16, 0, 0); } while (0)
; #define PG8_LDA(dst, b, h) do { _Pragma("unroll") for (int m = 0; m < 4; ++m) _Pragma("unroll") for (int k = 0; k < 2; ++k) dst[m][k] = *(const PG8_LAS bf16x8*)(lds + PG8_SA(b, h) + aoff + m * 2048 + k * 1024); } while (0)
; #define PG8_LDB(dst, b, h) do { _Pragma("unroll") for (int n = 0; n < 2; ++n) _Pragma("unroll") for (int k = 0; k < 2; ++k) dst[n][k] = *(const PG8_LAS bf16x8*)(lds + PG8_SB(b, h) + boff + n * 2048 + k * 1024); } while (0)
; #define PG8_MMA(ai, bj, At, Bt) do { __builtin_amdgcn_s_setprio(1); _Pragma("unroll") for (int m = 0; m < 4; ++m) _Pragma("unroll") for (int n = 0; n < 2; ++n) _Pragma("unroll") for (int k = 0; k < 2; ++k) \
;         acc[ai][bj][m][n] = __builtin_amdgcn_mfma_f32_16x16x32_bf16(Bt[n][k], At[m][k], acc[ai][bj][m][n], 0, 0, 0); __builtin_amdgcn_s_setprio(0); } while (0)
; #define PG8_WAIT_V(n) asm volatile("s_waitcnt vmcnt(" #n ")" ::: "memory")
; #define PG8_BAR __builtin_amdgcn_s_barrier()
; template <class Epi, class Sched, bool ALIGN_EPI = false, bool SP2 = false>
; __device__ __forceinline__ void gemm_phase(PG8_LAS unsigned char* lds, const Gemm g, const Sched& S, const Epi& E, const int tid_in) {
;     ...
;         for (int t = 0; t < nt; t += 2) {
;             const bool last = (t == nt - 2);
;             const char* a1 = cA + (size_t)(t + 1) * kstep;
;             const char* a2 = last ? nA : cA + (size_t)(t + 2) * kstep; const char* b2 = last ? nB : cB + (size_t)(t + 2) * kstep;
;             const char* a3 = a2 + kstep; const char* b3 = b2 + kstep;
;             if (last && has_next) S.a_ready(nxt);
;             if constexpr (SP2) {
;             PG8_LDB(B0, 0, 0); PG8_LDB(B1, 0, 1); PG8_SCHED; PG8_LDA(At, 0, 0); PG8_STAGE(PG8_SA(1, 1), a1 + hstep, voffA);
;             PG8_WAIT_V(8); PG8_WAIT_L(0); PG8_BAR; PG8_MMA(0, 0, At, B0); PG8_MMA(0, 1, At, B1); PG8_BAR; PG8_SCHED;
;             PG8_LDA(At, 0, 1); PG8_STAGE(PG8_SB(0, 0), b2, voffB); PG8_STAGE(PG8_SB(0, 1), b2 + hstep, voffB); PG8_STAGE(PG8_SA(0, 0), a2, voffA);
;             PG8_WAIT_V(8); PG8_WAIT_L(0); PG8_BAR; PG8_MMA(1, 0, At, B0); PG8_MMA(1, 1, At, B1); PG8_BAR; PG8_SCHED;
.LBB0_177:
	s_add_i32 s51, s12, 2
	s_add_u32 s52, s10, 0x80
	s_addc_u32 s13, s11, 0
	s_add_i32 s54, 0, 0x10000
	s_cmp_eq_u32 s31, s12
	s_cselect_b32 s13, s1, s13
	s_cselect_b32 s12, s0, s52
	s_cselect_b32 s53, s45, s15
	s_cselect_b32 s52, s44, s14
	s_cselect_b64 vcc, exec, 0
	s_add_i32 s55, 0, 0x14000
	v_add_u32_e32 v138, s54, v247
	v_add_u32_e32 v154, s55, v247
	ds_read_b128 v[126:129], v138
	ds_read_b128 v[130:133], v138 offset:1024
	ds_read_b128 v[134:137], v138 offset:2048
	ds_read_b128 v[138:141], v138 offset:3072
	ds_read_b128 v[142:145], v154
	ds_read_b128 v[146:149], v154 offset:1024
	ds_read_b128 v[150:153], v154 offset:2048
	ds_read_b128 v[154:157], v154 offset:3072
	v_lshl_add_u64 v[214:215], s[10:11], 0, v[206:207]
	s_add_i32 m0, s18, 0xc000
	ds_read_b128 v[158:161], v249
	ds_read_b128 v[162:165], v249 offset:1024
	ds_read_b128 v[170:173], v249 offset:2048
	ds_read_b128 v[178:181], v249 offset:3072
	ds_read_b128 v[182:185], v249 offset:4096
	ds_read_b128 v[186:189], v249 offset:5120
	ds_read_b128 v[190:193], v249 offset:6144
	ds_read_b128 v[210:213], v249 offset:7168
	global_load_lds_dwordx4 v[214:215], off
	v_lshl_add_u64 v[214:215], s[10:11], 0, v[208:209]
	s_add_i32 m0, s18, 0xe000
	s_nop 0
	global_load_lds_dwordx4 v[214:215], off
	s_nop 0
	s_waitcnt vmcnt(8)
	s_waitcnt lgkmcnt(0)
	s_barrier
	v_mfma_f32_16x16x32_bf16 v[174:177], v[126:129], v[158:161], v[174:177]
	v_mfma_f32_16x16x32_bf16 v[174:177], v[130:133], v[162:165], v[174:177]
	v_mfma_f32_16x16x32_bf16 v[114:117], v[126:129], v[170:173], v[114:117]
	v_mfma_f32_16x16x32_bf16 v[114:117], v[130:133], v[178:181], v[114:117]
	v_mfma_f32_16x16x32_bf16 v[98:101], v[126:129], v[182:185], v[98:101]
	v_mfma_f32_16x16x32_bf16 v[98:101], v[130:133], v[186:189], v[98:101]
	v_mfma_f32_16x16x32_bf16 v[82:85], v[126:129], v[190:193], v[82:85]
	v_mfma_f32_16x16x32_bf16 v[82:85], v[130:133], v[210:213], v[82:85]
	v_mfma_f32_16x16x32_bf16 v[166:169], v[134:137], v[158:161], v[166:169]
	v_mfma_f32_16x16x32_bf16 v[166:169], v[138:141], v[162:165], v[166:169]
	v_mfma_f32_16x16x32_bf16 v[110:113], v[134:137], v[170:173], v[110:113]
	v_mfma_f32_16x16x32_bf16 v[110:113], v[138:141], v[178:181], v[110:113]
	v_mfma_f32_16x16x32_bf16 v[94:97], v[134:137], v[182:185], v[94:97]
	v_mfma_f32_16x16x32_bf16 v[94:97], v[138:141], v[186:189], v[94:97]
	v_mfma_f32_16x16x32_bf16 v[78:81], v[134:137], v[190:193], v[78:81]
	v_mfma_f32_16x16x32_bf16 v[78:81], v[138:141], v[210:213], v[78:81]
	v_mfma_f32_16x16x32_bf16 v[122:125], v[142:145], v[158:161], v[122:125]
	v_mfma_f32_16x16x32_bf16 v[122:125], v[146:149], v[162:165], v[122:125]
	v_mfma_f32_16x16x32_bf16 v[106:109], v[142:145], v[170:173], v[106:109]
	v_mfma_f32_16x16x32_bf16 v[106:109], v[146:149], v[178:181], v[106:109]
	v_mfma_f32_16x16x32_bf16 v[90:93], v[142:145], v[182:185], v[90:93]
	v_mfma_f32_16x16x32_bf16 v[90:93], v[146:149], v[186:189], v[90:93]
	v_mfma_f32_16x16x32_bf16 v[74:77], v[142:145], v[190:193], v[74:77]
	v_mfma_f32_16x16x32_bf16 v[74:77], v[146:149], v[210:213], v[74:77]
	v_mfma_f32_16x16x32_bf16 v[118:121], v[150:153], v[158:161], v[118:121]
	v_mfma_f32_16x16x32_bf16 v[118:121], v[154:157], v[162:165], v[118:121]
	v_mfma_f32_16x16x32_bf16 v[102:105], v[150:153], v[170:173], v[102:105]
	v_mfma_f32_16x16x32_bf16 v[102:105], v[154:157], v[178:181], v[102:105]
	v_mfma_f32_16x16x32_bf16 v[86:89], v[150:153], v[182:185], v[86:89]
	v_mfma_f32_16x16x32_bf16 v[86:89], v[154:157], v[186:189], v[86:89]
	v_mfma_f32_16x16x32_bf16 v[70:73], v[150:153], v[190:193], v[70:73]
	v_mfma_f32_16x16x32_bf16 v[70:73], v[154:157], v[210:213], v[70:73]
	s_barrier
	s_add_i32 s54, s54, s17
	v_lshl_add_u64 v[214:215], s[52:53], 0, v[202:203]
	s_mov_b32 m0, s54
	ds_read_b128 v[158:161], v249 offset:16384
	ds_read_b128 v[162:165], v249 offset:17408
	ds_read_b128 v[170:173], v249 offset:18432
	ds_read_b128 v[178:181], v249 offset:19456
	ds_read_b128 v[182:185], v249 offset:20480
	ds_read_b128 v[186:189], v249 offset:21504
	ds_read_b128 v[190:193], v249 offset:22528
	ds_read_b128 v[210:213], v249 offset:23552
	s_cbranch_vccnz .Lrt_skip_1
	global_load_lds_dwordx4 v[214:215], off
	s_add_i32 m0, s54, 0x2000
	v_lshl_add_u64 v[216:217], s[52:53], 0, v[198:199]
	s_add_u32 s52, s52, s62
	s_addc_u32 s53, s53, 0
	s_add_i32 s54, s55, s17
	global_load_lds_dwordx4 v[216:217], off
	v_lshl_add_u64 v[218:219], s[52:53], 0, v[202:203]
	s_mov_b32 m0, s54
	v_lshl_add_u64 v[220:221], s[52:53], 0, v[198:199]
	global_load_lds_dwordx4 v[218:219], off
	s_add_i32 m0, s54, 0x2000
	v_lshl_add_u64 v[222:223], s[12:13], 0, v[204:205]
	global_load_lds_dwordx4 v[220:221], off
	s_mov_b32 m0, s18
	v_lshl_add_u64 v[224:225], s[12:13], 0, v[200:201]
	global_load_lds_dwordx4 v[222:223], off
	s_mov_b32 m0, s19
	s_nop 0
	global_load_lds_dwordx4 v[224:225], off
	s_waitcnt vmcnt(8)
	s_branch .Lrt_join_1

; #define PG8_STAGE(bufoff, gbase, voff) do { _Pragma("unroll") for (int _i = 0; _i < 2; ++_i) \
;         __builtin_amdgcn_global_load_lds((const unsigned*)((const char*)(gbase) + (voff)[_i]), (PG8_LAS unsigned*)(lds + (bufoff) + ldsw + _i * 8192), 16, 0, 0); } while (0)
; #define PG8_LDA(dst, b, h) do { _Pragma("unroll") for (int m = 0; m < 4; ++m) _Pragma("unroll") for (int k = 0; k < 2; ++k) dst[m][k] = *(const PG8_LAS bf16x8*)(lds + PG8_SA(b, h) + aoff + m * 2048 + k * 1024); } while (0)
; #define PG8_LDB(dst, b, h) do { _Pragma("unroll") for (int n = 0; n < 2; ++n) _Pragma("unroll") for (int k = 0; k < 2; ++k) dst[n][k] = *(const PG8_LAS bf16x8*)(lds + PG8_SB(b, h) + boff + n * 2048 + k * 1024); } while (0)
; #define PG8_MMA(ai, bj, At, Bt) do { __builtin_amdgcn_s_setprio(1); _Pragma("unroll") for (int m = 0; m < 4; ++m) _Pragma("unroll") for (int n = 0; n < 2; ++n) _Pragma("unroll") for (int k = 0; k < 2; ++k) \
;         acc[ai][bj][m][n] = __builtin_amdgcn_mfma_f32_16x16x32_bf16(Bt[n][k], At[m][k], acc[ai][bj][m][n], 0, 0, 0); __builtin_amdgcn_s_setprio(0); } while (0)
; #define PG8_WAIT_V(n) asm volatile("s_waitcnt vmcnt(" #n ")" ::: "memory")
; #define PG8_WAIT_L(n) asm volatile("s_waitcnt lgkmcnt(" #n ")" ::: "memory")
; #define PG8_BAR __builtin_amdgcn_s_barrier()
; #define PG8_SCHED __builtin_amdgcn_sched_barrier(0)
; template <class Epi, class Sched, bool ALIGN_EPI = false, bool SP2 = false>
; __device__ __forceinline__ void gemm_phase(PG8_LAS unsigned char* lds, const Gemm g, const Sched& S, const Epi& E, const int tid_in) {
;     ...
;             PG8_WAIT_V(8); PG8_WAIT_L(0); PG8_BAR; PG8_MMA(1, 0, At, B0); PG8_MMA(1, 1, At, B1); PG8_BAR; PG8_SCHED;
;             PG8_LDB(B0, 1, 0); PG8_LDB(B1, 1, 1); PG8_SCHED; PG8_LDA(At, 1, 0); PG8_STAGE(PG8_SA(0, 1), a2 + hstep, voffA);
;             PG8_WAIT_V(8); PG8_WAIT_L(0); PG8_BAR; PG8_MMA(0, 0, At, B0); PG8_MMA(0, 1, At, B1); PG8_BAR; PG8_SCHED;
.Lrt_join_1:
	s_waitcnt lgkmcnt(0)
	s_barrier
	v_mfma_f32_16x16x32_bf16 v[66:69], v[126:129], v[158:161], v[66:69]
	v_mfma_f32_16x16x32_bf16 v[66:69], v[130:133], v[162:165], v[66:69]
	v_mfma_f32_16x16x32_bf16 v[50:53], v[126:129], v[170:173], v[50:53]
	v_mfma_f32_16x16x32_bf16 v[50:53], v[130:133], v[178:181], v[50:53]
	v_mfma_f32_16x16x32_bf16 v[34:37], v[126:129], v[182:185], v[34:37]
	v_mfma_f32_16x16x32_bf16 v[34:37], v[130:133], v[186:189], v[34:37]
	v_mfma_f32_16x16x32_bf16 v[18:21], v[126:129], v[190:193], v[18:21]
	v_mfma_f32_16x16x32_bf16 v[18:21], v[130:133], v[210:213], v[18:21]
	v_mfma_f32_16x16x32_bf16 v[62:65], v[134:137], v[158:161], v[62:65]
	v_mfma_f32_16x16x32_bf16 v[62:65], v[138:141], v[162:165], v[62:65]
	v_mfma_f32_16x16x32_bf16 v[46:49], v[134:137], v[170:173], v[46:49]
	v_mfma_f32_16x16x32_bf16 v[46:49], v[138:141], v[178:181], v[46:49]
	v_mfma_f32_16x16x32_bf16 v[30:33], v[134:137], v[182:185], v[30:33]
	v_mfma_f32_16x16x32_bf16 v[30:33], v[138:141], v[186:189], v[30:33]
	v_mfma_f32_16x16x32_bf16 v[14:17], v[134:137], v[190:193], v[14:17]
	v_mfma_f32_16x16x32_bf16 v[14:17], v[138:141], v[210:213], v[14:17]
	v_mfma_f32_16x16x32_bf16 v[58:61], v[142:145], v[158:161], v[58:61]
	v_mfma_f32_16x16x32_bf16 v[58:61], v[146:149], v[162:165], v[58:61]
	v_mfma_f32_16x16x32_bf16 v[42:45], v[142:145], v[170:173], v[42:45]
	v_mfma_f32_16x16x32_bf16 v[42:45], v[146:149], v[178:181], v[42:45]
	v_mfma_f32_16x16x32_bf16 v[26:29], v[142:145], v[182:185], v[26:29]
	v_mfma_f32_16x16x32_bf16 v[26:29], v[146:149], v[186:189], v[26:29]
	v_mfma_f32_16x16x32_bf16 v[10:13], v[142:145], v[190:193], v[10:13]
	v_mfma_f32_16x16x32_bf16 v[10:13], v[146:149], v[210:213], v[10:13]
	v_mfma_f32_16x16x32_bf16 v[54:57], v[150:153], v[158:161], v[54:57]
	v_mfma_f32_16x16x32_bf16 v[54:57], v[154:157], v[162:165], v[54:57]
	v_mfma_f32_16x16x32_bf16 v[38:41], v[150:153], v[170:173], v[38:41]
	v_mfma_f32_16x16x32_bf16 v[38:41], v[154:157], v[178:181], v[38:41]
	v_mfma_f32_16x16x32_bf16 v[22:25], v[150:153], v[182:185], v[22:25]
	v_mfma_f32_16x16x32_bf16 v[22:25], v[154:157], v[186:189], v[22:25]
	v_mfma_f32_16x16x32_bf16 v[6:9], v[150:153], v[190:193], v[6:9]
	v_mfma_f32_16x16x32_bf16 v[6:9], v[154:157], v[210:213], v[6:9]
	s_barrier
	s_add_i32 s52, 0, 0x18000
	s_add_i32 s53, 0, 0x1c000
	v_add_u32_e32 v138, s52, v247
	v_add_u32_e32 v154, s53, v247
	ds_read_b128 v[126:129], v138
	ds_read_b128 v[130:133], v138 offset:1024
	ds_read_b128 v[134:137], v138 offset:2048
	ds_read_b128 v[138:141], v138 offset:3072
	ds_read_b128 v[142:145], v154
	ds_read_b128 v[146:149], v154 offset:1024
	ds_read_b128 v[150:153], v154 offset:2048
	ds_read_b128 v[154:157], v154 offset:3072
	s_add_u32 s12, s12, s62
	s_addc_u32 s13, s13, 0
	s_mov_b32 m0, s22
	v_lshl_add_u64 v[226:227], s[12:13], 0, v[204:205]
	ds_read_b128 v[158:161], v249 offset:32768
	ds_read_b128 v[162:165], v249 offset:33792
	ds_read_b128 v[170:173], v249 offset:34816
	ds_read_b128 v[178:181], v249 offset:35840
	ds_read_b128 v[182:185], v249 offset:36864
	ds_read_b128 v[186:189], v249 offset:37888
	ds_read_b128 v[190:193], v249 offset:38912
	ds_read_b128 v[210:213], v249 offset:39936
	s_cbranch_vccnz .Lrt_skip_2
	global_load_lds_dwordx4 v[226:227], off
	v_lshl_add_u64 v[226:227], s[12:13], 0, v[200:201]
	s_mov_b32 m0, s23
	s_nop 0
	global_load_lds_dwordx4 v[226:227], off
	s_waitcnt vmcnt(8)
	s_branch .Lrt_join_2

; __device__ __forceinline__ unsigned cvt_pk_bf16(float lo, float hi) { unsigned r; asm volatile("v_cvt_pk_bf16_f32 %0, %1, %2" : "=v"(r) : "v"(lo), "v"(hi)); return r; }
;     __device__ __forceinline__ void operator()(const f32x4 (&acc)[2][2][4][2], const Unit& u, int wr, int wc, int fr, int fq) const {
;         const int row0 = u.pm * BM + wr * 64 + fr, col0 = u.pn * BM + wc * 32 + 8 * fq;
;         u32x4 xv[2][4][2];
; #pragma unroll
;         for (int ai = 0; ai < 2; ++ai)
; #pragma unroll
;             for (int m = 0; m < 4; ++m)
; #pragma unroll
;                 for (int bj = 0; bj < 2; ++bj) xv[ai][m][bj] = *(const u32x4*)(xb + (size_t)(row0 + ai * HALF + m * 16) * 1024 + col0 + bj * HALF);
;         float ssv[2][4];
; #pragma unroll
;         for (int ai = 0; ai < 2; ++ai)
; #pragma unroll
;             for (int m = 0; m < 4; ++m) {
;                 const int row = row0 + ai * HALF + m * 16;
;                 float ss = 0.f;
; #pragma unroll
;                 for (int bj = 0; bj < 2; ++bj) {
;                     const u32x4 xo = xv[ai][m][bj]; u32x4 w;
; #pragma unroll
;                     for (int k = 0; k < 4; ++k) {
;                         const float a0 = __uint_as_float(xo[k] << 16) + acc[ai][bj][m][k >> 1][(k & 1) * 2] * scale, a1 = __uint_as_float(xo[k] & 0xffff0000u) + acc[ai][bj][m][k >> 1][(k & 1) * 2 + 1] * scale;
;                         const unsigned p = cvt_pk_bf16(a0, a1); w[k] = p;
;                         const float r0 = __uint_as_float(p << 16), r1 = __uint_as_float(p & 0xffff0000u); ss += r0 * r0 + r1 * r1;
;                     }
;                     *(u32x4*)(xb + (size_t)row * 1024 + col0 + bj * HALF) = w;
.LBB0_180:
	v_lshl_or_b32 v126, s49, 8, v248
	v_lshl_add_u32 v210, s50, 8, v246
	v_ashrrev_i32_e32 v127, 31, v126
	v_lshlrev_b64 v[212:213], 1, v[126:127]
	v_ashrrev_i32_e32 v211, 31, v210
	v_lshl_add_u64 v[126:127], s[84:85], 0, v[212:213]
	v_lshlrev_b64 v[228:229], 11, v[210:211]
	v_lshl_add_u64 v[128:129], v[126:127], 0, v[228:229]
	global_load_dwordx4 v[238:241], v[128:129], off
	global_load_dwordx4 v[190:193], v[128:129], off offset:256
	v_or_b32_e32 v128, 16, v210
	v_ashrrev_i32_e32 v129, 31, v128
	v_lshlrev_b64 v[226:227], 11, v[128:129]
	v_lshl_add_u64 v[128:129], v[126:127], 0, v[226:227]
	global_load_dwordx4 v[186:189], v[128:129], off
	global_load_dwordx4 v[182:185], v[128:129], off offset:256
	v_or_b32_e32 v128, 32, v210
	v_ashrrev_i32_e32 v129, 31, v128
	v_lshlrev_b64 v[224:225], 11, v[128:129]
	v_lshl_add_u64 v[128:129], v[126:127], 0, v[224:225]
	global_load_dwordx4 v[178:181], v[128:129], off
	global_load_dwordx4 v[170:173], v[128:129], off offset:256
	v_or_b32_e32 v128, 48, v210
	v_ashrrev_i32_e32 v129, 31, v128
	s_mov_b64 s[10:11], 0x40000
	v_lshlrev_b64 v[222:223], 11, v[128:129]
	v_lshl_add_u64 v[220:221], v[228:229], 0, s[10:11]
	s_mov_b64 s[10:11], 0x48000
	v_lshl_add_u64 v[128:129], v[126:127], 0, v[222:223]
	v_lshl_add_u64 v[218:219], v[228:229], 0, s[10:11]
	s_mov_b64 s[10:11], 0x50000
	global_load_dwordx4 v[162:165], v[128:129], off
	global_load_dwordx4 v[154:157], v[128:129], off offset:256
	v_lshl_add_u64 v[128:129], v[126:127], 0, v[220:221]
	v_lshl_add_u64 v[216:217], v[228:229], 0, s[10:11]
	s_mov_b64 s[10:11], 0x58000
	global_load_dwordx4 v[158:161], v[128:129], off
	global_load_dwordx4 v[150:153], v[128:129], off offset:256
	v_lshl_add_u64 v[128:129], v[126:127], 0, v[218:219]
	v_lshl_add_u64 v[214:215], v[228:229], 0, s[10:11]
	global_load_dwordx4 v[146:149], v[128:129], off
	global_load_dwordx4 v[142:145], v[128:129], off offset:256
	v_lshl_add_u64 v[128:129], v[126:127], 0, v[216:217]
	v_lshl_add_u64 v[126:127], v[126:127], 0, v[214:215]
	global_load_dwordx4 v[138:141], v[128:129], off
	global_load_dwordx4 v[134:137], v[128:129], off offset:256
	global_load_dwordx4 v[130:133], v[126:127], off
	s_nop 0
	global_load_dwordx4 v[126:129], v[126:127], off offset:256
	s_waitcnt vmcnt(15)
	v_lshlrev_b32_e32 v250, 16, v238
	v_fmac_f32_e32 v250, v2, v174
	v_and_b32_e32 v174, 0xffff0000, v238
	v_fmac_f32_e32 v174, v2, v175
	v_cvt_pk_bf16_f32 v174, v250, v174
	s_nop 0
	v_and_b32_e32 v238, 0xffff0000, v174
	v_lshlrev_b32_e32 v175, 16, v174
	v_mul_f32_e32 v238, v238, v238
	v_fmac_f32_e32 v238, v175, v175
	v_lshlrev_b32_e32 v175, 16, v239
	v_fmac_f32_e32 v175, v2, v176
	v_and_b32_e32 v176, 0xffff0000, v239
	v_fmac_f32_e32 v176, v2, v177
	v_cvt_pk_bf16_f32 v175, v175, v176
	s_nop 0
	v_and_b32_e32 v177, 0xffff0000, v175
	v_lshlrev_b32_e32 v176, 16, v175
	v_mul_f32_e32 v177, v177, v177
	v_fmac_f32_e32 v177, v176, v176
	v_lshlrev_b32_e32 v176, 16, v240
	v_fmac_f32_e32 v176, v2, v166
	v_and_b32_e32 v166, 0xffff0000, v240
	v_fmac_f32_e32 v166, v2, v167
	v_cvt_pk_bf16_f32 v176, v176, v166
	v_add_f32_e32 v177, v238, v177
	v_and_b32_e32 v167, 0xffff0000, v176
	v_lshlrev_b32_e32 v166, 16, v176
	v_mul_f32_e32 v167, v167, v167
	v_fmac_f32_e32 v167, v166, v166
	v_add_f32_e32 v166, v177, v167
	v_lshlrev_b32_e32 v167, 16, v241
	v_fmac_f32_e32 v167, v2, v168
	v_and_b32_e32 v168, 0xffff0000, v241
	v_fmac_f32_e32 v168, v2, v169
	v_cvt_pk_bf16_f32 v177, v167, v168
	s_waitcnt vmcnt(14)
	v_lshlrev_b32_e32 v169, 16, v190
	v_and_b32_e32 v168, 0xffff0000, v177
	v_lshlrev_b32_e32 v167, 16, v177
	v_mul_f32_e32 v168, v168, v168
	v_fmac_f32_e32 v168, v167, v167
	v_add_f32_e32 v168, v166, v168
	v_lshl_add_u64 v[166:167], s[84:85], 0, v[228:229]
	v_fmac_f32_e32 v169, v2, v122
	v_and_b32_e32 v122, 0xffff0000, v190
	v_lshl_add_u64 v[166:167], v[166:167], 0, v[212:213]
	v_fmac_f32_e32 v122, v2, v123
	global_store_dwordx4 v[166:167], v[174:177], off
	v_cvt_pk_bf16_f32 v122, v169, v122
	s_nop 0
	v_and_b32_e32 v169, 0xffff0000, v122
	v_lshlrev_b32_e32 v123, 16, v122
	v_mul_f32_e32 v169, v169, v169
	v_fmac_f32_e32 v169, v123, v123
	v_lshlrev_b32_e32 v123, 16, v191
	v_fmac_f32_e32 v123, v2, v124
	v_and_b32_e32 v124, 0xffff0000, v191
	v_fmac_f32_e32 v124, v2, v125
	v_cvt_pk_bf16_f32 v123, v123, v124
	v_add_f32_e32 v168, v168, v169
	v_and_b32_e32 v125, 0xffff0000, v123
	v_lshlrev_b32_e32 v124, 16, v123
	v_mul_f32_e32 v125, v125, v125
	v_fmac_f32_e32 v125, v124, v124
	v_lshlrev_b32_e32 v124, 16, v192
	v_fmac_f32_e32 v124, v2, v118
	v_and_b32_e32 v118, 0xffff0000, v192
	v_fmac_f32_e32 v118, v2, v119
	v_cvt_pk_bf16_f32 v124, v124, v118
	v_add_f32_e32 v125, v168, v125
	v_and_b32_e32 v119, 0xffff0000, v124
	v_lshlrev_b32_e32 v118, 16, v124
	v_mul_f32_e32 v119, v119, v119
	v_fmac_f32_e32 v119, v118, v118
	v_add_f32_e32 v118, v125, v119
	v_lshlrev_b32_e32 v119, 16, v193
	v_fmac_f32_e32 v119, v2, v120
	v_and_b32_e32 v120, 0xffff0000, v193
	v_fmac_f32_e32 v120, v2, v121
	v_cvt_pk_bf16_f32 v125, v119, v120
	global_store_dwordx4 v[166:167], v[122:125], off offset:256
	v_and_b32_e32 v120, 0xffff0000, v125
	v_lshlrev_b32_e32 v119, 16, v125
	v_mul_f32_e32 v120, v120, v120
	v_fmac_f32_e32 v120, v119, v119
	s_waitcnt vmcnt(15)
; __device__ __forceinline__ unsigned cvt_pk_bf16(float lo, float hi) { unsigned r; asm volatile("v_cvt_pk_bf16_f32 %0, %1, %2" : "=v"(r) : "v"(lo), "v"(hi)); return r; }
;     __device__ __forceinline__ void operator()(const f32x4 (&acc)[2][2][4][2], const Unit& u, int wr, int wc, int fr, int fq) const {
;     ...
;             for (int m = 0; m < 4; ++m) {
;                 const int row = row0 + ai * HALF + m * 16;
;                 float ss = 0.f;
; #pragma unroll
;                 for (int bj = 0; bj < 2; ++bj) {
;                     const u32x4 xo = xv[ai][m][bj]; u32x4 w;
; #pragma unroll
;                     for (int k = 0; k < 4; ++k) {
;                         const float a0 = __uint_as_float(xo[k] << 16) + acc[ai][bj][m][k >> 1][(k & 1) * 2] * scale, a1 = __uint_as_float(xo[k] & 0xffff0000u) + acc[ai][bj][m][k >> 1][(k & 1) * 2 + 1] * scale;
;                         const unsigned p = cvt_pk_bf16(a0, a1); w[k] = p;
;                         const float r0 = __uint_as_float(p << 16), r1 = __uint_as_float(p & 0xffff0000u); ss += r0 * r0 + r1 * r1;
;                     }
;                     *(u32x4*)(xb + (size_t)row * 1024 + col0 + bj * HALF) = w;
;                 }
;                 ssv[ai][m] = ss;
;             }
	v_lshlrev_b32_e32 v119, 16, v186
	v_fmac_f32_e32 v119, v2, v114
	v_and_b32_e32 v114, 0xffff0000, v186
	v_fmac_f32_e32 v114, v2, v115
	v_cvt_pk_bf16_f32 v114, v119, v114
	v_add_f32_e32 v118, v118, v120
	v_and_b32_e32 v119, 0xffff0000, v114
	v_lshlrev_b32_e32 v115, 16, v114
	v_mul_f32_e32 v119, v119, v119
	v_fmac_f32_e32 v119, v115, v115
	v_lshlrev_b32_e32 v115, 16, v187
	v_fmac_f32_e32 v115, v2, v116
	v_and_b32_e32 v116, 0xffff0000, v187
	v_fmac_f32_e32 v116, v2, v117
	v_cvt_pk_bf16_f32 v115, v115, v116
	s_nop 0
	v_and_b32_e32 v117, 0xffff0000, v115
	v_lshlrev_b32_e32 v116, 16, v115
	v_mul_f32_e32 v117, v117, v117
	v_fmac_f32_e32 v117, v116, v116
	v_lshlrev_b32_e32 v116, 16, v188
	v_fmac_f32_e32 v116, v2, v110
	v_and_b32_e32 v110, 0xffff0000, v188
	v_fmac_f32_e32 v110, v2, v111
	v_cvt_pk_bf16_f32 v116, v116, v110
	v_add_f32_e32 v117, v119, v117
	v_and_b32_e32 v111, 0xffff0000, v116
	v_lshlrev_b32_e32 v110, 16, v116
	v_mul_f32_e32 v111, v111, v111
	v_fmac_f32_e32 v111, v110, v110
	v_add_f32_e32 v110, v117, v111
	v_lshlrev_b32_e32 v111, 16, v189
	v_fmac_f32_e32 v111, v2, v112
	v_and_b32_e32 v112, 0xffff0000, v189
	v_fmac_f32_e32 v112, v2, v113
	v_cvt_pk_bf16_f32 v117, v111, v112
	s_waitcnt vmcnt(14)
	v_lshlrev_b32_e32 v113, 16, v182
	v_and_b32_e32 v112, 0xffff0000, v117
	v_lshlrev_b32_e32 v111, 16, v117
	v_mul_f32_e32 v112, v112, v112
	v_fmac_f32_e32 v112, v111, v111
	v_add_f32_e32 v112, v110, v112
	v_lshl_add_u64 v[110:111], s[84:85], 0, v[226:227]
	v_fmac_f32_e32 v113, v2, v106
	v_and_b32_e32 v106, 0xffff0000, v182
	v_lshl_add_u64 v[110:111], v[110:111], 0, v[212:213]
	v_fmac_f32_e32 v106, v2, v107
	global_store_dwordx4 v[110:111], v[114:117], off
	v_cvt_pk_bf16_f32 v106, v113, v106
	s_nop 0
	v_and_b32_e32 v113, 0xffff0000, v106
	v_lshlrev_b32_e32 v107, 16, v106
	v_mul_f32_e32 v113, v113, v113
	v_fmac_f32_e32 v113, v107, v107
	v_lshlrev_b32_e32 v107, 16, v183
	v_fmac_f32_e32 v107, v2, v108
	v_and_b32_e32 v108, 0xffff0000, v183
	v_fmac_f32_e32 v108, v2, v109
	v_cvt_pk_bf16_f32 v107, v107, v108
	v_add_f32_e32 v112, v112, v113
	v_and_b32_e32 v109, 0xffff0000, v107
	v_lshlrev_b32_e32 v108, 16, v107
	v_mul_f32_e32 v109, v109, v109
	v_fmac_f32_e32 v109, v108, v108
	v_lshlrev_b32_e32 v108, 16, v184
	v_fmac_f32_e32 v108, v2, v102
	v_and_b32_e32 v102, 0xffff0000, v184
	v_fmac_f32_e32 v102, v2, v103
	v_cvt_pk_bf16_f32 v108, v108, v102
	v_add_f32_e32 v109, v112, v109
	v_and_b32_e32 v103, 0xffff0000, v108
	v_lshlrev_b32_e32 v102, 16, v108
	v_mul_f32_e32 v103, v103, v103
	v_fmac_f32_e32 v103, v102, v102
	v_add_f32_e32 v102, v109, v103
	v_lshlrev_b32_e32 v103, 16, v185
	v_fmac_f32_e32 v103, v2, v104
	v_and_b32_e32 v104, 0xffff0000, v185
	v_fmac_f32_e32 v104, v2, v105
	v_cvt_pk_bf16_f32 v109, v103, v104
	global_store_dwordx4 v[110:111], v[106:109], off offset:256
	v_and_b32_e32 v104, 0xffff0000, v109
	v_lshlrev_b32_e32 v103, 16, v109
	v_mul_f32_e32 v104, v104, v104
	v_fmac_f32_e32 v104, v103, v103
	s_waitcnt vmcnt(15)
	v_lshlrev_b32_e32 v103, 16, v178
	v_fmac_f32_e32 v103, v2, v98
	v_and_b32_e32 v98, 0xffff0000, v178
	v_fmac_f32_e32 v98, v2, v99
	v_cvt_pk_bf16_f32 v98, v103, v98
	v_add_f32_e32 v102, v102, v104
	v_and_b32_e32 v103, 0xffff0000, v98
	v_lshlrev_b32_e32 v99, 16, v98
	v_mul_f32_e32 v103, v103, v103
	v_fmac_f32_e32 v103, v99, v99
	v_lshlrev_b32_e32 v99, 16, v179
	v_fmac_f32_e32 v99, v2, v100
	v_and_b32_e32 v100, 0xffff0000, v179
	v_fmac_f32_e32 v100, v2, v101
	v_cvt_pk_bf16_f32 v99, v99, v100
	s_nop 0
	v_and_b32_e32 v101, 0xffff0000, v99
	v_lshlrev_b32_e32 v100, 16, v99
	v_mul_f32_e32 v101, v101, v101
	v_fmac_f32_e32 v101, v100, v100
	v_lshlrev_b32_e32 v100, 16, v180
	v_fmac_f32_e32 v100, v2, v94
	v_and_b32_e32 v94, 0xffff0000, v180
	v_fmac_f32_e32 v94, v2, v95
	v_cvt_pk_bf16_f32 v100, v100, v94
	v_add_f32_e32 v101, v103, v101
	v_and_b32_e32 v95, 0xffff0000, v100
	v_lshlrev_b32_e32 v94, 16, v100
	v_mul_f32_e32 v95, v95, v95
	v_fmac_f32_e32 v95, v94, v94
	v_add_f32_e32 v94, v101, v95
	v_lshlrev_b32_e32 v95, 16, v181
	v_fmac_f32_e32 v95, v2, v96
	v_and_b32_e32 v96, 0xffff0000, v181
	v_fmac_f32_e32 v96, v2, v97
	v_cvt_pk_bf16_f32 v101, v95, v96
	s_waitcnt vmcnt(14)
	v_lshlrev_b32_e32 v97, 16, v170
	v_and_b32_e32 v96, 0xffff0000, v101
	v_lshlrev_b32_e32 v95, 16, v101
	v_mul_f32_e32 v96, v96, v96
	v_fmac_f32_e32 v96, v95, v95
	v_add_f32_e32 v96, v94, v96
	v_lshl_add_u64 v[94:95], s[84:85], 0, v[224:225]
	v_fmac_f32_e32 v97, v2, v90
	v_and_b32_e32 v90, 0xffff0000, v170
	v_lshl_add_u64 v[94:95], v[94:95], 0, v[212:213]
	v_fmac_f32_e32 v90, v2, v91
	global_store_dwordx4 v[94:95], v[98:101], off
	v_cvt_pk_bf16_f32 v90, v97, v90
	s_nop 0
	v_and_b32_e32 v97, 0xffff0000, v90
	v_lshlrev_b32_e32 v91, 16, v90
	v_mul_f32_e32 v97, v97, v97
	v_fmac_f32_e32 v97, v91, v91
	v_lshlrev_b32_e32 v91, 16, v171
	v_fmac_f32_e32 v91, v2, v92
	v_and_b32_e32 v92, 0xffff0000, v171
	v_fmac_f32_e32 v92, v2, v93
	v_cvt_pk_bf16_f32 v91, v91, v92
	v_add_f32_e32 v96, v96, v97
	v_and_b32_e32 v93, 0xffff0000, v91
	v_lshlrev_b32_e32 v92, 16, v91
	v_mul_f32_e32 v93, v93, v93
	v_fmac_f32_e32 v93, v92, v92
	v_lshlrev_b32_e32 v92, 16, v172
	v_fmac_f32_e32 v92, v2, v86
	v_and_b32_e32 v86, 0xffff0000, v172
	v_fmac_f32_e32 v86, v2, v87
	v_cvt_pk_bf16_f32 v92, v92, v86
	v_add_f32_e32 v93, v96, v93
	v_and_b32_e32 v87, 0xffff0000, v92
	v_lshlrev_b32_e32 v86, 16, v92
	v_mul_f32_e32 v87, v87, v87
	v_fmac_f32_e32 v87, v86, v86
	v_add_f32_e32 v86, v93, v87
	v_lshlrev_b32_e32 v87, 16, v173
	v_fmac_f32_e32 v87, v2, v88
	v_and_b32_e32 v88, 0xffff0000, v173
	v_fmac_f32_e32 v88, v2, v89
	v_cvt_pk_bf16_f32 v93, v87, v88
	global_store_dwordx4 v[94:95], v[90:93], off offset:256
	v_and_b32_e32 v88, 0xffff0000, v93
	v_lshlrev_b32_e32 v87, 16, v93
	v_mul_f32_e32 v88, v88, v88
	v_fmac_f32_e32 v88, v87, v87
	s_waitcnt vmcnt(15)
; __device__ __forceinline__ unsigned cvt_pk_bf16(float lo, float hi) { unsigned r; asm volatile("v_cvt_pk_bf16_f32 %0, %1, %2" : "=v"(r) : "v"(lo), "v"(hi)); return r; }
;     __device__ __forceinline__ void operator()(const f32x4 (&acc)[2][2][4][2], const Unit& u, int wr, int wc, int fr, int fq) const {
;     ...
;             for (int m = 0; m < 4; ++m) {
;                 const int row = row0 + ai * HALF + m * 16;
;                 float ss = 0.f;
; #pragma unroll
;                 for (int bj = 0; bj < 2; ++bj) {
;                     const u32x4 xo = xv[ai][m][bj]; u32x4 w;
; #pragma unroll
;                     for (int k = 0; k < 4; ++k) {
;                         const float a0 = __uint_as_float(xo[k] << 16) + acc[ai][bj][m][k >> 1][(k & 1) * 2] * scale, a1 = __uint_as_float(xo[k] & 0xffff0000u) + acc[ai][bj][m][k >> 1][(k & 1) * 2 + 1] * scale;
;                         const unsigned p = cvt_pk_bf16(a0, a1); w[k] = p;
;                         const float r0 = __uint_as_float(p << 16), r1 = __uint_as_float(p & 0xffff0000u); ss += r0 * r0 + r1 * r1;
;                     }
;                     *(u32x4*)(xb + (size_t)row * 1024 + col0 + bj * HALF) = w;
;                 }
;                 ssv[ai][m] = ss;
;             }
	v_lshlrev_b32_e32 v87, 16, v162
	v_fmac_f32_e32 v87, v2, v82
	v_and_b32_e32 v82, 0xffff0000, v162
	v_fmac_f32_e32 v82, v2, v83
	v_cvt_pk_bf16_f32 v82, v87, v82
	v_add_f32_e32 v86, v86, v88
	v_and_b32_e32 v87, 0xffff0000, v82
	v_lshlrev_b32_e32 v83, 16, v82
	v_mul_f32_e32 v87, v87, v87
	v_fmac_f32_e32 v87, v83, v83
	v_lshlrev_b32_e32 v83, 16, v163
	v_fmac_f32_e32 v83, v2, v84
	v_and_b32_e32 v84, 0xffff0000, v163
	v_fmac_f32_e32 v84, v2, v85
	v_cvt_pk_bf16_f32 v83, v83, v84
	s_nop 0
	v_and_b32_e32 v85, 0xffff0000, v83
	v_lshlrev_b32_e32 v84, 16, v83
	v_mul_f32_e32 v85, v85, v85
	v_fmac_f32_e32 v85, v84, v84
	v_lshlrev_b32_e32 v84, 16, v164
	v_fmac_f32_e32 v84, v2, v78
	v_and_b32_e32 v78, 0xffff0000, v164
	v_fmac_f32_e32 v78, v2, v79
	v_cvt_pk_bf16_f32 v84, v84, v78
	v_add_f32_e32 v85, v87, v85
	v_and_b32_e32 v79, 0xffff0000, v84
	v_lshlrev_b32_e32 v78, 16, v84
	v_mul_f32_e32 v79, v79, v79
	v_fmac_f32_e32 v79, v78, v78
	v_add_f32_e32 v78, v85, v79
	v_lshlrev_b32_e32 v79, 16, v165
	v_fmac_f32_e32 v79, v2, v80
	v_and_b32_e32 v80, 0xffff0000, v165
	v_fmac_f32_e32 v80, v2, v81
	v_cvt_pk_bf16_f32 v85, v79, v80
	s_waitcnt vmcnt(14)
	v_lshlrev_b32_e32 v81, 16, v154
	v_and_b32_e32 v80, 0xffff0000, v85
	v_lshlrev_b32_e32 v79, 16, v85
	v_mul_f32_e32 v80, v80, v80
	v_fmac_f32_e32 v80, v79, v79
	v_add_f32_e32 v80, v78, v80
	v_lshl_add_u64 v[78:79], s[84:85], 0, v[222:223]
	v_fmac_f32_e32 v81, v2, v74
	v_and_b32_e32 v74, 0xffff0000, v154
	v_lshl_add_u64 v[78:79], v[78:79], 0, v[212:213]
	v_fmac_f32_e32 v74, v2, v75
	global_store_dwordx4 v[78:79], v[82:85], off
	v_cvt_pk_bf16_f32 v74, v81, v74
	s_nop 0
	v_and_b32_e32 v81, 0xffff0000, v74
	v_lshlrev_b32_e32 v75, 16, v74
	v_mul_f32_e32 v81, v81, v81
	v_fmac_f32_e32 v81, v75, v75
	v_lshlrev_b32_e32 v75, 16, v155
	v_fmac_f32_e32 v75, v2, v76
	v_and_b32_e32 v76, 0xffff0000, v155
	v_fmac_f32_e32 v76, v2, v77
	v_cvt_pk_bf16_f32 v75, v75, v76
	v_add_f32_e32 v80, v80, v81
	v_and_b32_e32 v77, 0xffff0000, v75
	v_lshlrev_b32_e32 v76, 16, v75
	v_mul_f32_e32 v77, v77, v77
	v_fmac_f32_e32 v77, v76, v76
	v_lshlrev_b32_e32 v76, 16, v156
	v_fmac_f32_e32 v76, v2, v70
	v_and_b32_e32 v70, 0xffff0000, v156
	v_fmac_f32_e32 v70, v2, v71
	v_cvt_pk_bf16_f32 v76, v76, v70
	v_add_f32_e32 v77, v80, v77
	v_and_b32_e32 v71, 0xffff0000, v76
	v_lshlrev_b32_e32 v70, 16, v76
	v_mul_f32_e32 v71, v71, v71
	v_fmac_f32_e32 v71, v70, v70
	v_add_f32_e32 v70, v77, v71
	v_lshlrev_b32_e32 v71, 16, v157
	v_fmac_f32_e32 v71, v2, v72
	v_and_b32_e32 v72, 0xffff0000, v157
	v_fmac_f32_e32 v72, v2, v73
	v_cvt_pk_bf16_f32 v77, v71, v72
	global_store_dwordx4 v[78:79], v[74:77], off offset:256
	v_and_b32_e32 v72, 0xffff0000, v77
	v_lshlrev_b32_e32 v71, 16, v77
	v_mul_f32_e32 v72, v72, v72
	v_fmac_f32_e32 v72, v71, v71
	s_waitcnt vmcnt(15)
	v_lshlrev_b32_e32 v71, 16, v158
	v_fmac_f32_e32 v71, v2, v66
	v_and_b32_e32 v66, 0xffff0000, v158
	v_fmac_f32_e32 v66, v2, v67
	v_cvt_pk_bf16_f32 v66, v71, v66
	v_add_f32_e32 v70, v70, v72
	v_and_b32_e32 v71, 0xffff0000, v66
	v_lshlrev_b32_e32 v67, 16, v66
	v_mul_f32_e32 v71, v71, v71
	v_fmac_f32_e32 v71, v67, v67
	v_lshlrev_b32_e32 v67, 16, v159
	v_fmac_f32_e32 v67, v2, v68
	v_and_b32_e32 v68, 0xffff0000, v159
	v_fmac_f32_e32 v68, v2, v69
	v_cvt_pk_bf16_f32 v67, v67, v68
	s_nop 0
	v_and_b32_e32 v69, 0xffff0000, v67
	v_lshlrev_b32_e32 v68, 16, v67
	v_mul_f32_e32 v69, v69, v69
	v_fmac_f32_e32 v69, v68, v68
	v_lshlrev_b32_e32 v68, 16, v160
	v_fmac_f32_e32 v68, v2, v62
	v_and_b32_e32 v62, 0xffff0000, v160
	v_fmac_f32_e32 v62, v2, v63
	v_cvt_pk_bf16_f32 v68, v68, v62
	v_add_f32_e32 v69, v71, v69
	v_and_b32_e32 v63, 0xffff0000, v68
	v_lshlrev_b32_e32 v62, 16, v68
	v_mul_f32_e32 v63, v63, v63
	v_fmac_f32_e32 v63, v62, v62
	v_add_f32_e32 v62, v69, v63
	v_lshlrev_b32_e32 v63, 16, v161
	v_fmac_f32_e32 v63, v2, v64
	v_and_b32_e32 v64, 0xffff0000, v161
	v_fmac_f32_e32 v64, v2, v65
	v_cvt_pk_bf16_f32 v69, v63, v64
	s_waitcnt vmcnt(14)
	v_lshlrev_b32_e32 v65, 16, v150
	v_and_b32_e32 v64, 0xffff0000, v69
	v_lshlrev_b32_e32 v63, 16, v69
	v_mul_f32_e32 v64, v64, v64
	v_fmac_f32_e32 v64, v63, v63
	v_add_f32_e32 v64, v62, v64
	v_lshl_add_u64 v[62:63], s[84:85], 0, v[220:221]
	v_fmac_f32_e32 v65, v2, v58
	v_and_b32_e32 v58, 0xffff0000, v150
	v_lshl_add_u64 v[62:63], v[62:63], 0, v[212:213]
	v_fmac_f32_e32 v58, v2, v59
	global_store_dwordx4 v[62:63], v[66:69], off
	v_cvt_pk_bf16_f32 v58, v65, v58
	s_nop 0
	v_and_b32_e32 v65, 0xffff0000, v58
	v_lshlrev_b32_e32 v59, 16, v58
	v_mul_f32_e32 v65, v65, v65
	v_fmac_f32_e32 v65, v59, v59
	v_lshlrev_b32_e32 v59, 16, v151
	v_fmac_f32_e32 v59, v2, v60
	v_and_b32_e32 v60, 0xffff0000, v151
	v_fmac_f32_e32 v60, v2, v61
	v_cvt_pk_bf16_f32 v59, v59, v60
	v_add_f32_e32 v64, v64, v65
	v_and_b32_e32 v61, 0xffff0000, v59
	v_lshlrev_b32_e32 v60, 16, v59
	v_mul_f32_e32 v61, v61, v61
	v_fmac_f32_e32 v61, v60, v60
	v_lshlrev_b32_e32 v60, 16, v152
	v_fmac_f32_e32 v60, v2, v54
	v_and_b32_e32 v54, 0xffff0000, v152
	v_fmac_f32_e32 v54, v2, v55
	v_cvt_pk_bf16_f32 v60, v60, v54
	v_add_f32_e32 v61, v64, v61
	v_and_b32_e32 v55, 0xffff0000, v60
	v_lshlrev_b32_e32 v54, 16, v60
	v_mul_f32_e32 v55, v55, v55
	v_fmac_f32_e32 v55, v54, v54
	v_add_f32_e32 v54, v61, v55
	v_lshlrev_b32_e32 v55, 16, v153
	v_fmac_f32_e32 v55, v2, v56
	v_and_b32_e32 v56, 0xffff0000, v153
	v_fmac_f32_e32 v56, v2, v57
	v_cvt_pk_bf16_f32 v61, v55, v56
	global_store_dwordx4 v[62:63], v[58:61], off offset:256
	v_and_b32_e32 v56, 0xffff0000, v61
	v_lshlrev_b32_e32 v55, 16, v61
	v_mul_f32_e32 v56, v56, v56
	v_fmac_f32_e32 v56, v55, v55
	s_waitcnt vmcnt(15)
; __device__ __forceinline__ unsigned cvt_pk_bf16(float lo, float hi) { unsigned r; asm volatile("v_cvt_pk_bf16_f32 %0, %1, %2" : "=v"(r) : "v"(lo), "v"(hi)); return r; }
;     __device__ __forceinline__ void operator()(const f32x4 (&acc)[2][2][4][2], const Unit& u, int wr, int wc, int fr, int fq) const {
;     ...
;             for (int m = 0; m < 4; ++m) {
;                 const int row = row0 + ai * HALF + m * 16;
;                 float ss = 0.f;
; #pragma unroll
;                 for (int bj = 0; bj < 2; ++bj) {
;                     const u32x4 xo = xv[ai][m][bj]; u32x4 w;
; #pragma unroll
;                     for (int k = 0; k < 4; ++k) {
;                         const float a0 = __uint_as_float(xo[k] << 16) + acc[ai][bj][m][k >> 1][(k & 1) * 2] * scale, a1 = __uint_as_float(xo[k] & 0xffff0000u) + acc[ai][bj][m][k >> 1][(k & 1) * 2 + 1] * scale;
;                         const unsigned p = cvt_pk_bf16(a0, a1); w[k] = p;
;                         const float r0 = __uint_as_float(p << 16), r1 = __uint_as_float(p & 0xffff0000u); ss += r0 * r0 + r1 * r1;
;                     }
;                     *(u32x4*)(xb + (size_t)row * 1024 + col0 + bj * HALF) = w;
;                 }
;                 ssv[ai][m] = ss;
;             }
	v_lshlrev_b32_e32 v55, 16, v146
	v_fmac_f32_e32 v55, v2, v50
	v_and_b32_e32 v50, 0xffff0000, v146
	v_fmac_f32_e32 v50, v2, v51
	v_cvt_pk_bf16_f32 v50, v55, v50
	v_add_f32_e32 v54, v54, v56
	v_and_b32_e32 v55, 0xffff0000, v50
	v_lshlrev_b32_e32 v51, 16, v50
	v_mul_f32_e32 v55, v55, v55
	v_fmac_f32_e32 v55, v51, v51
	v_lshlrev_b32_e32 v51, 16, v147
	v_fmac_f32_e32 v51, v2, v52
	v_and_b32_e32 v52, 0xffff0000, v147
	v_fmac_f32_e32 v52, v2, v53
	v_cvt_pk_bf16_f32 v51, v51, v52
	s_nop 0
	v_and_b32_e32 v53, 0xffff0000, v51
	v_lshlrev_b32_e32 v52, 16, v51
	v_mul_f32_e32 v53, v53, v53
	v_fmac_f32_e32 v53, v52, v52
	v_lshlrev_b32_e32 v52, 16, v148
	v_fmac_f32_e32 v52, v2, v46
	v_and_b32_e32 v46, 0xffff0000, v148
	v_fmac_f32_e32 v46, v2, v47
	v_cvt_pk_bf16_f32 v52, v52, v46
	v_add_f32_e32 v53, v55, v53
	v_and_b32_e32 v47, 0xffff0000, v52
	v_lshlrev_b32_e32 v46, 16, v52
	v_mul_f32_e32 v47, v47, v47
	v_fmac_f32_e32 v47, v46, v46
	v_add_f32_e32 v46, v53, v47
	v_lshlrev_b32_e32 v47, 16, v149
	v_fmac_f32_e32 v47, v2, v48
	v_and_b32_e32 v48, 0xffff0000, v149
	v_fmac_f32_e32 v48, v2, v49
	v_cvt_pk_bf16_f32 v53, v47, v48
	s_waitcnt vmcnt(14)
	v_lshlrev_b32_e32 v49, 16, v142
	v_and_b32_e32 v48, 0xffff0000, v53
	v_lshlrev_b32_e32 v47, 16, v53
	v_mul_f32_e32 v48, v48, v48
	v_fmac_f32_e32 v48, v47, v47
	v_add_f32_e32 v48, v46, v48
	v_lshl_add_u64 v[46:47], s[84:85], 0, v[218:219]
	v_fmac_f32_e32 v49, v2, v42
	v_and_b32_e32 v42, 0xffff0000, v142
	v_lshl_add_u64 v[46:47], v[46:47], 0, v[212:213]
	v_fmac_f32_e32 v42, v2, v43
	global_store_dwordx4 v[46:47], v[50:53], off
	v_cvt_pk_bf16_f32 v42, v49, v42
	s_nop 0
	v_and_b32_e32 v49, 0xffff0000, v42
	v_lshlrev_b32_e32 v43, 16, v42
	v_mul_f32_e32 v49, v49, v49
	v_fmac_f32_e32 v49, v43, v43
	v_lshlrev_b32_e32 v43, 16, v143
	v_fmac_f32_e32 v43, v2, v44
	v_and_b32_e32 v44, 0xffff0000, v143
	v_fmac_f32_e32 v44, v2, v45
	v_cvt_pk_bf16_f32 v43, v43, v44
	v_add_f32_e32 v48, v48, v49
	v_and_b32_e32 v45, 0xffff0000, v43
	v_lshlrev_b32_e32 v44, 16, v43
	v_mul_f32_e32 v45, v45, v45
	v_fmac_f32_e32 v45, v44, v44
	v_lshlrev_b32_e32 v44, 16, v144
	v_fmac_f32_e32 v44, v2, v38
	v_and_b32_e32 v38, 0xffff0000, v144
	v_fmac_f32_e32 v38, v2, v39
	v_cvt_pk_bf16_f32 v44, v44, v38
	v_add_f32_e32 v45, v48, v45
	v_and_b32_e32 v39, 0xffff0000, v44
	v_lshlrev_b32_e32 v38, 16, v44
	v_mul_f32_e32 v39, v39, v39
	v_fmac_f32_e32 v39, v38, v38
	v_add_f32_e32 v38, v45, v39
	v_lshlrev_b32_e32 v39, 16, v145
	v_fmac_f32_e32 v39, v2, v40
	v_and_b32_e32 v40, 0xffff0000, v145
	v_fmac_f32_e32 v40, v2, v41
	v_cvt_pk_bf16_f32 v45, v39, v40
	global_store_dwordx4 v[46:47], v[42:45], off offset:256
	v_and_b32_e32 v40, 0xffff0000, v45
	v_lshlrev_b32_e32 v39, 16, v45
	v_mul_f32_e32 v40, v40, v40
	v_fmac_f32_e32 v40, v39, v39
	s_waitcnt vmcnt(15)
	v_lshlrev_b32_e32 v39, 16, v138
	v_fmac_f32_e32 v39, v2, v34
	v_and_b32_e32 v34, 0xffff0000, v138
	v_fmac_f32_e32 v34, v2, v35
	v_cvt_pk_bf16_f32 v34, v39, v34
	v_add_f32_e32 v38, v38, v40
	v_and_b32_e32 v39, 0xffff0000, v34
	v_lshlrev_b32_e32 v35, 16, v34
	v_mul_f32_e32 v39, v39, v39
	v_fmac_f32_e32 v39, v35, v35
	v_lshlrev_b32_e32 v35, 16, v139
	v_fmac_f32_e32 v35, v2, v36
	v_and_b32_e32 v36, 0xffff0000, v139
	v_fmac_f32_e32 v36, v2, v37
	v_cvt_pk_bf16_f32 v35, v35, v36
	s_nop 0
	v_and_b32_e32 v37, 0xffff0000, v35
	v_lshlrev_b32_e32 v36, 16, v35
	v_mul_f32_e32 v37, v37, v37
	v_fmac_f32_e32 v37, v36, v36
	v_lshlrev_b32_e32 v36, 16, v140
	v_fmac_f32_e32 v36, v2, v30
	v_and_b32_e32 v30, 0xffff0000, v140
	v_fmac_f32_e32 v30, v2, v31
	v_cvt_pk_bf16_f32 v36, v36, v30
	v_add_f32_e32 v37, v39, v37
	v_and_b32_e32 v31, 0xffff0000, v36
	v_lshlrev_b32_e32 v30, 16, v36
	v_mul_f32_e32 v31, v31, v31
	v_fmac_f32_e32 v31, v30, v30
	v_add_f32_e32 v30, v37, v31
	v_lshlrev_b32_e32 v31, 16, v141
	v_fmac_f32_e32 v31, v2, v32
	v_and_b32_e32 v32, 0xffff0000, v141
	v_fmac_f32_e32 v32, v2, v33
	v_cvt_pk_bf16_f32 v37, v31, v32
	s_waitcnt vmcnt(14)
	v_lshlrev_b32_e32 v33, 16, v134
	v_and_b32_e32 v32, 0xffff0000, v37
	v_lshlrev_b32_e32 v31, 16, v37
	v_mul_f32_e32 v32, v32, v32
	v_fmac_f32_e32 v32, v31, v31
	v_add_f32_e32 v32, v30, v32
	v_lshl_add_u64 v[30:31], s[84:85], 0, v[216:217]
	v_fmac_f32_e32 v33, v2, v26
	v_and_b32_e32 v26, 0xffff0000, v134
	v_lshl_add_u64 v[30:31], v[30:31], 0, v[212:213]
	v_fmac_f32_e32 v26, v2, v27
	global_store_dwordx4 v[30:31], v[34:37], off
	v_cvt_pk_bf16_f32 v26, v33, v26
	s_nop 0
	v_and_b32_e32 v33, 0xffff0000, v26
	v_lshlrev_b32_e32 v27, 16, v26
	v_mul_f32_e32 v33, v33, v33
	v_fmac_f32_e32 v33, v27, v27
	v_lshlrev_b32_e32 v27, 16, v135
	v_fmac_f32_e32 v27, v2, v28
	v_and_b32_e32 v28, 0xffff0000, v135
	v_fmac_f32_e32 v28, v2, v29
	v_cvt_pk_bf16_f32 v27, v27, v28
	v_add_f32_e32 v32, v32, v33
	v_and_b32_e32 v29, 0xffff0000, v27
	v_lshlrev_b32_e32 v28, 16, v27
	v_mul_f32_e32 v29, v29, v29
	v_fmac_f32_e32 v29, v28, v28
	v_lshlrev_b32_e32 v28, 16, v136
	v_fmac_f32_e32 v28, v2, v22
	v_and_b32_e32 v22, 0xffff0000, v136
	v_fmac_f32_e32 v22, v2, v23
	v_cvt_pk_bf16_f32 v28, v28, v22
	v_add_f32_e32 v29, v32, v29
	v_and_b32_e32 v23, 0xffff0000, v28
	v_lshlrev_b32_e32 v22, 16, v28
	v_mul_f32_e32 v23, v23, v23
	v_fmac_f32_e32 v23, v22, v22
	v_add_f32_e32 v22, v29, v23
	v_lshlrev_b32_e32 v23, 16, v137
	v_fmac_f32_e32 v23, v2, v24
	v_and_b32_e32 v24, 0xffff0000, v137
	v_fmac_f32_e32 v24, v2, v25
	v_cvt_pk_bf16_f32 v29, v23, v24
	global_store_dwordx4 v[30:31], v[26:29], off offset:256
	v_and_b32_e32 v24, 0xffff0000, v29
	v_lshlrev_b32_e32 v23, 16, v29
	v_mul_f32_e32 v24, v24, v24
	v_fmac_f32_e32 v24, v23, v23
	s_waitcnt vmcnt(15)
; __device__ __forceinline__ unsigned cvt_pk_bf16(float lo, float hi) { unsigned r; asm volatile("v_cvt_pk_bf16_f32 %0, %1, %2" : "=v"(r) : "v"(lo), "v"(hi)); return r; }
;     __device__ __forceinline__ void operator()(const f32x4 (&acc)[2][2][4][2], const Unit& u, int wr, int wc, int fr, int fq) const {
;     ...
;             for (int m = 0; m < 4; ++m) {
;                 const int row = row0 + ai * HALF + m * 16;
;                 float ss = 0.f;
; #pragma unroll
;                 for (int bj = 0; bj < 2; ++bj) {
;                     const u32x4 xo = xv[ai][m][bj]; u32x4 w;
; #pragma unroll
;                     for (int k = 0; k < 4; ++k) {
;                         const float a0 = __uint_as_float(xo[k] << 16) + acc[ai][bj][m][k >> 1][(k & 1) * 2] * scale, a1 = __uint_as_float(xo[k] & 0xffff0000u) + acc[ai][bj][m][k >> 1][(k & 1) * 2 + 1] * scale;
;                         const unsigned p = cvt_pk_bf16(a0, a1); w[k] = p;
;                         const float r0 = __uint_as_float(p << 16), r1 = __uint_as_float(p & 0xffff0000u); ss += r0 * r0 + r1 * r1;
;                     }
;                     *(u32x4*)(xb + (size_t)row * 1024 + col0 + bj * HALF) = w;
;                 }
;                 ssv[ai][m] = ss;
;             }
; #pragma unroll
;         for (int ai = 0; ai < 2; ++ai)
; #pragma unroll
;             for (int m = 0; m < 4; ++m) ssv[ai][m] += __shfl_xor(ssv[ai][m], 16);
; #pragma unroll
;         for (int ai = 0; ai < 2; ++ai)
; #pragma unroll
;             for (int m = 0; m < 4; ++m) ssv[ai][m] += __shfl_xor(ssv[ai][m], 32);
;         if (fq == 0 && fin) {
; #pragma unroll
;             for (int ai = 0; ai < 2; ++ai)
; #pragma unroll
;                 for (int m = 0; m < 4; ++m) unsafeAtomicAdd(rowss + row0 + ai * HALF + m * 16, ssv[ai][m]);
;         }
	v_lshlrev_b32_e32 v23, 16, v130
	v_fmac_f32_e32 v23, v2, v18
	v_and_b32_e32 v18, 0xffff0000, v130
	v_fmac_f32_e32 v18, v2, v19
	v_cvt_pk_bf16_f32 v18, v23, v18
	v_add_f32_e32 v22, v22, v24
	v_and_b32_e32 v238, 64, v232
	v_xor_b32_e32 v239, 16, v232
	v_add_u32_e32 v238, 64, v238
	v_xor_b32_e32 v240, 32, v232
	v_cmp_lt_i32_e32 vcc, v239, v238
	s_nop 1
	v_cndmask_b32_e32 v239, v232, v239, vcc
	v_cmp_lt_i32_e32 vcc, v240, v238
	v_lshlrev_b32_e32 v239, 2, v239
	s_nop 0
	v_cndmask_b32_e32 v240, v232, v240, vcc
	v_lshlrev_b32_e32 v240, 2, v240
	ds_bpermute_b32 v190, v239, v118
	ds_bpermute_b32 v191, v239, v102
	ds_bpermute_b32 v192, v239, v86
	ds_bpermute_b32 v193, v239, v70
	ds_bpermute_b32 v186, v239, v54
	ds_bpermute_b32 v187, v239, v38
	ds_bpermute_b32 v188, v239, v22
	s_waitcnt lgkmcnt(0)
	v_add_f32_e32 v190, v118, v190
	v_add_f32_e32 v191, v102, v191
	v_add_f32_e32 v192, v86, v192
	v_add_f32_e32 v193, v70, v193
	v_add_f32_e32 v186, v54, v186
	v_add_f32_e32 v187, v38, v187
	v_add_f32_e32 v188, v22, v188
	ds_bpermute_b32 v182, v240, v190
	ds_bpermute_b32 v183, v240, v191
	ds_bpermute_b32 v184, v240, v192
	ds_bpermute_b32 v185, v240, v193
	ds_bpermute_b32 v178, v240, v186
	ds_bpermute_b32 v179, v240, v187
	ds_bpermute_b32 v180, v240, v188
	v_lshl_add_u64 v[170:171], v[210:211], 2, s[8:9]
	s_waitcnt lgkmcnt(0)
	s_and_saveexec_b64 s[52:53], s[38:39]
	v_add_f32_e32 v190, v190, v182
	v_add_f32_e32 v191, v191, v183
	v_add_f32_e32 v192, v192, v184
	v_add_f32_e32 v193, v193, v185
	v_add_f32_e32 v186, v186, v178
	v_add_f32_e32 v187, v187, v179
	v_add_f32_e32 v188, v188, v180
	global_atomic_add_f32 v[170:171], v190, off
	global_atomic_add_f32 v[170:171], v191, off offset:64
	global_atomic_add_f32 v[170:171], v192, off offset:128
	global_atomic_add_f32 v[170:171], v193, off offset:192
	global_atomic_add_f32 v[170:171], v186, off offset:512
	global_atomic_add_f32 v[170:171], v187, off offset:576
	global_atomic_add_f32 v[170:171], v188, off offset:640
	s_or_b64 exec, exec, s[52:53]
	v_and_b32_e32 v23, 0xffff0000, v18
	v_lshlrev_b32_e32 v19, 16, v18
	v_mul_f32_e32 v23, v23, v23
	v_fmac_f32_e32 v23, v19, v19
	v_lshlrev_b32_e32 v19, 16, v131
	v_fmac_f32_e32 v19, v2, v20
	v_and_b32_e32 v20, 0xffff0000, v131
	v_fmac_f32_e32 v20, v2, v21
	v_cvt_pk_bf16_f32 v19, v19, v20
	s_nop 0
	v_and_b32_e32 v21, 0xffff0000, v19
	v_lshlrev_b32_e32 v20, 16, v19
	v_mul_f32_e32 v21, v21, v21
	v_fmac_f32_e32 v21, v20, v20
	v_lshlrev_b32_e32 v20, 16, v132
	v_fmac_f32_e32 v20, v2, v14
	v_and_b32_e32 v14, 0xffff0000, v132
	v_fmac_f32_e32 v14, v2, v15
	v_cvt_pk_bf16_f32 v20, v20, v14
	v_add_f32_e32 v21, v23, v21
	v_and_b32_e32 v15, 0xffff0000, v20
	v_lshlrev_b32_e32 v14, 16, v20
	v_mul_f32_e32 v15, v15, v15
	v_fmac_f32_e32 v15, v14, v14
	v_add_f32_e32 v14, v21, v15
	v_lshlrev_b32_e32 v15, 16, v133
	v_fmac_f32_e32 v15, v2, v16
	v_and_b32_e32 v16, 0xffff0000, v133
	v_fmac_f32_e32 v16, v2, v17
	v_cvt_pk_bf16_f32 v21, v15, v16
	s_waitcnt vmcnt(21)
	v_lshlrev_b32_e32 v17, 16, v126
	v_and_b32_e32 v16, 0xffff0000, v21
	v_lshlrev_b32_e32 v15, 16, v21
	v_mul_f32_e32 v16, v16, v16
	v_fmac_f32_e32 v16, v15, v15
	v_add_f32_e32 v16, v14, v16
	v_lshl_add_u64 v[14:15], s[84:85], 0, v[214:215]
	v_fmac_f32_e32 v17, v2, v10
	v_and_b32_e32 v10, 0xffff0000, v126
	v_lshl_add_u64 v[14:15], v[14:15], 0, v[212:213]
	v_fmac_f32_e32 v10, v2, v11
	global_store_dwordx4 v[14:15], v[18:21], off
	v_cvt_pk_bf16_f32 v10, v17, v10
	s_nop 0
	v_and_b32_e32 v17, 0xffff0000, v10
	v_lshlrev_b32_e32 v11, 16, v10
	v_mul_f32_e32 v17, v17, v17
	v_fmac_f32_e32 v17, v11, v11
	v_lshlrev_b32_e32 v11, 16, v127
	v_fmac_f32_e32 v11, v2, v12
	v_and_b32_e32 v12, 0xffff0000, v127
	v_fmac_f32_e32 v12, v2, v13
	v_cvt_pk_bf16_f32 v11, v11, v12
	v_add_f32_e32 v16, v16, v17
	v_and_b32_e32 v13, 0xffff0000, v11
	v_lshlrev_b32_e32 v12, 16, v11
	v_mul_f32_e32 v13, v13, v13
	v_fmac_f32_e32 v13, v12, v12
	v_lshlrev_b32_e32 v12, 16, v128
	v_fmac_f32_e32 v12, v2, v6
	v_and_b32_e32 v6, 0xffff0000, v128
	v_fmac_f32_e32 v6, v2, v7
	v_cvt_pk_bf16_f32 v12, v12, v6
	v_add_f32_e32 v13, v16, v13
	v_and_b32_e32 v7, 0xffff0000, v12
	v_lshlrev_b32_e32 v6, 16, v12
	v_mul_f32_e32 v7, v7, v7
	v_fmac_f32_e32 v7, v6, v6
	v_add_f32_e32 v6, v13, v7
	v_lshlrev_b32_e32 v7, 16, v129
	v_fmac_f32_e32 v7, v2, v8
	v_and_b32_e32 v8, 0xffff0000, v129
	v_fmac_f32_e32 v8, v2, v9
	v_cvt_pk_bf16_f32 v13, v7, v8
	global_store_dwordx4 v[14:15], v[10:13], off offset:256
	v_and_b32_e32 v8, 0xffff0000, v13
	v_lshlrev_b32_e32 v7, 16, v13
	v_mul_f32_e32 v8, v8, v8
	v_fmac_f32_e32 v8, v7, v7
	v_and_b32_e32 v7, 64, v232
	v_add_f32_e32 v16, v6, v8
	v_xor_b32_e32 v6, 16, v232
	v_add_u32_e32 v13, 64, v7
	v_cmp_lt_i32_e32 vcc, v6, v13
	v_xor_b32_e32 v15, 32, v232
	s_nop 0
	v_cndmask_b32_e32 v6, v232, v6, vcc
	v_lshlrev_b32_e32 v14, 2, v6
	ds_bpermute_b32 v14, v14, v16
	v_cmp_lt_i32_e32 vcc, v15, v13
	s_nop 1
	v_cndmask_b32_e32 v13, v232, v15, vcc
	s_waitcnt lgkmcnt(0)
	v_add_f32_e32 v14, v16, v14
	v_lshlrev_b32_e32 v21, 2, v13
	ds_bpermute_b32 v21, v21, v14
	s_and_saveexec_b64 s[10:11], s[38:39]
	s_movk_i32 s55, 0x1a00
	s_cbranch_execz .LBB0_182
	v_lshl_add_u64 v[6:7], v[210:211], 2, s[8:9]
	s_waitcnt lgkmcnt(0)
	v_add_f32_e32 v14, v14, v21
	global_atomic_add_f32 v[6:7], v14, off offset:704
